# grid barrier: non-leader workgroups poll the top generation word directly instead of the per-XCD generation word (one hop fewer)
# baseline (speedup 1.0000x reference)
; __device__ __forceinline__ unsigned xb_ld(unsigned* p)              { return __hip_atomic_load(p, __ATOMIC_RELAXED, __HIP_MEMORY_SCOPE_AGENT); }
; __device__ __forceinline__ unsigned xb_add(unsigned* p, unsigned v) { return __hip_atomic_fetch_add(p, v, __ATOMIC_RELAXED, __HIP_MEMORY_SCOPE_AGENT); }
; #define XB_SPIN(cond, bar) do { unsigned _sp = 0; while (cond) { __builtin_amdgcn_s_sleep(1); \
;     if ((++_sp & 255u) == 0u) { if (xb_ld(&(bar)[XB_TMO])) break; if (_sp > XB_SPIN_CAP) { atomicAdd(&(bar)[XB_TMO], 1u); break; } } } } while (0)
; __device__ __forceinline__ void xcd_barrier(unsigned* bar, volatile LAS unsigned* st) {
;     ...
;         const unsigned old = xb_add(&bar[XB_XSUB(x)], 1u);
;         const unsigned gen = old / nloc;
;         if (old + 1u == (gen + 1u) * nloc) {
;             __builtin_amdgcn_fence(__ATOMIC_RELEASE, "agent");
;             asm volatile("s_waitcnt vmcnt(0)" ::: "memory");
;             const unsigned og = xb_add(&bar[XB_TOP], 1u);
;             const unsigned tg = og / nx;
;             if (og + 1u == (tg + 1u) * nx) xb_add(&bar[XB_TOPGEN], 1u);
;             else XB_SPIN(xb_ld(&bar[XB_TOPGEN]) == tg, bar);
;             __builtin_amdgcn_fence(__ATOMIC_ACQUIRE, "agent");
;             xb_add(&bar[XB_XGEN(x)], 1u);
;             asm volatile("s_waitcnt vmcnt(0)" ::: "memory");
;         } else {
;             XB_SPIN(xb_ld(&bar[XB_XGEN(x)]) == gen, bar);
.LBB0_461:
	s_or_b64 exec, exec, s[12:13]
	v_cvt_f32_u32_e32 v5, v3
	s_waitcnt vmcnt(0)
	v_readfirstlane_b32 s10, v4
	v_sub_u32_e32 v4, 0, v3
	v_rcp_iflag_f32_e32 v5, v5
	v_add_u32_e32 v6, s10, v1
	v_mul_f32_e32 v5, 0x4f7ffffe, v5
	v_cvt_u32_f32_e32 v5, v5
	v_mul_lo_u32 v1, v4, v5
	v_mul_hi_u32 v1, v5, v1
	v_add_u32_e32 v1, v5, v1
	v_mul_hi_u32 v1, v6, v1
	v_mul_lo_u32 v4, v1, v3
	v_sub_u32_e32 v4, v6, v4
	v_add_u32_e32 v5, 1, v1
	v_cmp_ge_u32_e32 vcc, v4, v3
	s_nop 1
	v_cndmask_b32_e32 v1, v1, v5, vcc
	v_sub_u32_e32 v5, v4, v3
	v_cndmask_b32_e32 v4, v4, v5, vcc
	v_add_u32_e32 v5, 1, v1
	v_cmp_ge_u32_e32 vcc, v4, v3
	v_add_u32_e32 v4, 1, v6
	s_nop 0
	v_cndmask_b32_e32 v1, v1, v5, vcc
	v_mul_lo_u32 v5, v3, v1
	v_add_u32_e32 v3, v5, v3
	v_cmp_ne_u32_e32 vcc, v4, v3
	s_and_saveexec_b64 s[10:11], vcc
	s_xor_b64 s[10:11], exec, s[10:11]
	s_cbranch_execz .LBB0_475
	s_waitcnt lgkmcnt(0)
	s_add_u32 s14, s6, 0x3500
	s_addc_u32 s15, s7, 0
	global_load_dword v2, v0, s[14:15] sc1
	s_waitcnt vmcnt(0)
	v_cmp_eq_u32_e32 vcc, v2, v1
	s_and_saveexec_b64 s[12:13], vcc
	s_cbranch_execz .LBB0_474
	s_mov_b32 s26, 1
	s_mov_b64 s[16:17], 0
	s_branch .LBB0_465
